# P4 epilogue: gain vector loads hoisted ahead of the row-statistics exchange
# baseline (speedup 1.0000x reference)
.LBB0_635:
	s_or_b64 exec, exec, s[10:11]
	v_lshrrev_b32_e32 v128, 2, v231
	v_and_b32_e32 v128, 28, v128
	s_lshl_b32 s16, s6, 8
	v_lshl_or_b32 v128, s26, 5, v128
	s_add_i32 s7, s16, s7
	v_lshl_or_b32 v128, s8, 8, v128
	v_or_b32_e32 v130, s7, v144
	s_waitcnt lgkmcnt(0)
	v_ashrrev_i32_e32 v129, 31, v128
	v_lshl_add_u64 v[212:213], v[128:129], 2, s[82:83]
	global_load_dwordx4 v[204:207], v[212:213], off
	global_load_dwordx4 v[240:243], v[212:213], off offset:64
	v_lshl_add_u64 v[212:213], v[128:129], 2, s[84:85]
	global_load_dwordx4 v[244:247], v[212:213], off
	global_load_dwordx4 v[248:251], v[212:213], off offset:64
	global_load_dwordx4 v[252:255], v[212:213], off offset:512
	v_ashrrev_i32_e32 v131, 31, v130
	v_lshl_add_u64 v[134:135], v[128:129], 1, s[70:71]
	v_lshl_add_u64 v[136:137], v[130:131], 2, s[68:69]
	v_lshlrev_b64 v[138:139], 11, v[130:131]
	v_lshl_add_u64 v[138:139], v[134:135], 0, v[138:139]
	global_load_dword v230, v[136:137], off
	global_load_dwordx2 v[226:227], v[138:139], off
	global_load_dwordx2 v[236:237], v[138:139], off offset:32
	global_load_dwordx2 v[234:235], v[138:139], off offset:256
	v_or_b32_e32 v136, 16, v130
	v_ashrrev_i32_e32 v137, 31, v136
	v_lshl_add_u64 v[140:141], v[136:137], 2, s[68:69]
	v_lshlrev_b64 v[136:137], 11, v[136:137]
	v_lshl_add_u64 v[136:137], v[134:135], 0, v[136:137]
	global_load_dwordx2 v[232:233], v[138:139], off offset:288
	global_load_dword v218, v[140:141], off
	global_load_dwordx2 v[228:229], v[136:137], off
	global_load_dwordx2 v[224:225], v[136:137], off offset:32
	v_or_b32_e32 v138, 32, v130
	v_ashrrev_i32_e32 v139, 31, v138
	v_lshl_add_u64 v[140:141], v[138:139], 2, s[68:69]
	v_lshlrev_b64 v[138:139], 11, v[138:139]
	v_lshl_add_u64 v[138:139], v[134:135], 0, v[138:139]
	global_load_dwordx2 v[222:223], v[136:137], off offset:256
	global_load_dwordx2 v[220:221], v[136:137], off offset:288
	global_load_dword v202, v[140:141], off
	global_load_dwordx2 v[216:217], v[138:139], off
	v_or_b32_e32 v136, 48, v130
	v_ashrrev_i32_e32 v137, 31, v136
	v_lshl_add_u64 v[140:141], v[136:137], 2, s[68:69]
	v_lshlrev_b64 v[136:137], 11, v[136:137]
	v_lshl_add_u64 v[136:137], v[134:135], 0, v[136:137]
	global_load_dwordx2 v[214:215], v[138:139], off offset:32
	global_load_dwordx2 v[210:211], v[138:139], off offset:256
	global_load_dwordx2 v[208:209], v[138:139], off offset:288
	global_load_dword v182, v[140:141], off
	global_load_dwordx2 v[200:201], v[136:137], off
	global_load_dwordx2 v[194:195], v[136:137], off offset:32
	global_load_dwordx2 v[186:187], v[136:137], off offset:256
	global_load_dwordx2 v[184:185], v[136:137], off offset:288
	v_add_u32_e32 v136, 0x80, v130
	v_ashrrev_i32_e32 v137, 31, v136
	v_lshl_add_u64 v[138:139], v[136:137], 2, s[68:69]
	v_lshlrev_b64 v[136:137], 11, v[136:137]
	v_lshl_add_u64 v[136:137], v[134:135], 0, v[136:137]
	global_load_dword v170, v[138:139], off
	global_load_dwordx2 v[180:181], v[136:137], off
	global_load_dwordx2 v[178:179], v[136:137], off offset:32
	global_load_dwordx2 v[176:177], v[136:137], off offset:256
	v_add_u32_e32 v138, 0x90, v130
	v_ashrrev_i32_e32 v139, 31, v138
	v_lshl_add_u64 v[140:141], v[138:139], 2, s[68:69]
	v_lshlrev_b64 v[138:139], 11, v[138:139]
	v_lshl_add_u64 v[138:139], v[134:135], 0, v[138:139]
	global_load_dwordx2 v[174:175], v[136:137], off offset:288
	global_load_dword v160, v[140:141], off
	global_load_dwordx2 v[168:169], v[138:139], off
	global_load_dwordx2 v[166:167], v[138:139], off offset:32
	v_add_u32_e32 v136, 0xa0, v130
	v_ashrrev_i32_e32 v137, 31, v136
	v_add_u32_e32 v130, 0xb0, v130
	v_lshl_add_u64 v[140:141], v[136:137], 2, s[68:69]
	v_lshlrev_b64 v[136:137], 11, v[136:137]
	v_ashrrev_i32_e32 v131, 31, v130
	v_lshl_add_u64 v[136:137], v[134:135], 0, v[136:137]
	global_load_dwordx2 v[164:165], v[138:139], off offset:256
	global_load_dwordx2 v[162:163], v[138:139], off offset:288
	global_load_dword v150, v[140:141], off
	global_load_dwordx2 v[158:159], v[136:137], off
	v_lshl_add_u64 v[138:139], v[130:131], 2, s[68:69]
	v_lshlrev_b64 v[130:131], 11, v[130:131]
	v_lshl_add_u64 v[130:131], v[134:135], 0, v[130:131]
	global_load_dwordx2 v[156:157], v[136:137], off offset:32
	global_load_dwordx2 v[154:155], v[136:137], off offset:256
	global_load_dwordx2 v[152:153], v[136:137], off offset:288
	global_load_dword v140, v[138:139], off
	global_load_dwordx2 v[148:149], v[130:131], off
	global_load_dwordx2 v[146:147], v[130:131], off offset:32
	global_load_dwordx2 v[144:145], v[130:131], off offset:256
	global_load_dwordx2 v[142:143], v[130:131], off offset:288
	s_cmp_lg_u32 s63, 0
	s_cbranch_scc1 .LBB0_650
	s_memrealtime s[8:9]
	s_lshl_b32 s10, s6, 6
	s_ashr_i32 s11, s10, 31
	s_lshl_b64 s[10:11], s[10:11], 2
	s_add_u32 s10, s14, s10
	s_addc_u32 s11, s15, s11
	v_mov_b32_e32 v133, 0
	v_mov_b64_e32 v[130:131], 0x1e8481
	s_branch .LBB0_639

.LBB0_652:
	s_or_b64 exec, exec, s[2:3]
	v_lshlrev_b64 v[172:173], 2, v[128:129]
	s_waitcnt lgkmcnt(0)
	s_barrier
	v_lshl_add_u64 v[188:189], s[82:83], 0, v[172:173]
	v_mov_b32_e32 v190, v204
	v_mov_b32_e32 v191, v205
	v_mov_b32_e32 v192, v206
	v_mov_b32_e32 v193, v207
	v_mov_b32_e32 v196, v240
	v_mov_b32_e32 v197, v241
	v_mov_b32_e32 v198, v242
	v_mov_b32_e32 v199, v243
	v_or_b32_e32 v171, v171, v161
	v_lshl_add_u64 v[238:239], s[84:85], 0, v[172:173]
	v_mov_b32_e32 v136, v244
	v_mov_b32_e32 v137, v245
	v_mov_b32_e32 v138, v246
	v_mov_b32_e32 v139, v247
	v_mov_b32_e32 v132, v248
	v_mov_b32_e32 v133, v249
	v_mov_b32_e32 v134, v250
	v_mov_b32_e32 v135, v251
	v_mov_b32_e32 v128, v252
	v_mov_b32_e32 v129, v253
	v_mov_b32_e32 v130, v254
	v_mov_b32_e32 v131, v255
	s_waitcnt lgkmcnt(0)
	v_or_b32_e32 v171, v141, v171
	v_mov_b32_e32 v141, 0x7fc00000
	s_waitcnt vmcnt(0)
	v_div_scale_f32 v161, s[0:1], v190, v190, 1.0
	v_div_scale_f32 v203, s[0:1], v191, v191, 1.0
	v_rcp_f32_e32 v231, v161
	v_rcp_f32_e32 v244, v203
	v_div_scale_f32 v213, s[2:3], v192, v192, 1.0
	v_div_scale_f32 v219, s[2:3], v193, v193, 1.0
	v_rcp_f32_e32 v245, v213
	v_rcp_f32_e32 v246, v219
	v_fma_f32 v204, -v161, v231, 1.0
	v_fma_f32 v205, -v203, v244, 1.0
	v_div_scale_f32 v183, vcc, 1.0, v190, 1.0
	v_div_scale_f32 v212, s[0:1], 1.0, v191, 1.0
	v_fmac_f32_e32 v231, v204, v231
	v_fmac_f32_e32 v244, v205, v244
	v_mul_f32_e32 v240, v183, v231
	v_mul_f32_e32 v247, v212, v244
	v_fma_f32 v206, -v213, v245, 1.0
	v_fma_f32 v207, -v219, v246, 1.0
	v_fma_f32 v204, -v161, v240, v183
	v_fma_f32 v205, -v203, v247, v212
	v_fmac_f32_e32 v245, v206, v245
	v_fmac_f32_e32 v246, v207, v246
	v_fmac_f32_e32 v240, v204, v231
	v_fmac_f32_e32 v247, v205, v244
	global_load_dwordx4 v[204:207], v[188:189], off offset:512
	v_fma_f32 v161, -v161, v240, v183
	v_div_fmas_f32 v161, v161, v231, v240
	global_load_dwordx4 v[240:243], v[188:189], off offset:576
	v_div_scale_f32 v188, s[2:3], 1.0, v192, 1.0
	v_mul_f32_e32 v189, v188, v245
	v_fma_f32 v183, -v203, v247, v212
	v_fma_f32 v203, -v213, v189, v188
	s_mov_b64 vcc, s[0:1]
	v_fmac_f32_e32 v189, v203, v245
	v_div_fmas_f32 v183, v183, v244, v247
	v_div_scale_f32 v203, s[0:1], 1.0, v193, 1.0
	v_fma_f32 v188, -v213, v189, v188
	s_mov_b64 vcc, s[2:3]
	v_div_fmas_f32 v188, v188, v245, v189
	v_mul_f32_e32 v189, v203, v246
	v_fma_f32 v213, -v219, v189, v203
	v_fmac_f32_e32 v189, v213, v246
	v_div_scale_f32 v212, s[4:5], v196, v196, 1.0
	v_fma_f32 v203, -v219, v189, v203
	s_mov_b64 vcc, s[0:1]
	v_div_scale_f32 v219, s[4:5], v197, v197, 1.0
	v_div_fmas_f32 v189, v203, v246, v189
	v_rcp_f32_e32 v203, v212
	v_div_fixup_f32 v190, v161, v190, 1.0
	v_rcp_f32_e32 v161, v219
	v_div_fixup_f32 v192, v188, v192, 1.0
	v_fma_f32 v188, -v212, v203, 1.0
	v_div_scale_f32 v213, s[2:3], 1.0, v196, 1.0
	v_div_fixup_f32 v193, v189, v193, 1.0
	v_fma_f32 v189, -v219, v161, 1.0
	v_fmac_f32_e32 v203, v188, v203
	v_div_fixup_f32 v191, v183, v191, 1.0
	v_div_scale_f32 v183, s[0:1], 1.0, v197, 1.0
	v_fmac_f32_e32 v161, v189, v161
	v_mul_f32_e32 v188, v213, v203
	v_mul_f32_e32 v189, v183, v161
	v_fma_f32 v231, -v212, v188, v213
	v_fmac_f32_e32 v188, v231, v203
	v_fma_f32 v231, -v219, v189, v183
	v_fmac_f32_e32 v189, v231, v161
	v_div_scale_f32 v231, s[4:5], v198, v198, 1.0
	v_fma_f32 v212, -v212, v188, v213
	v_rcp_f32_e32 v213, v231
	s_mov_b64 vcc, s[2:3]
	v_fma_f32 v183, -v219, v189, v183
	v_div_fmas_f32 v188, v212, v203, v188
	s_mov_b64 vcc, s[0:1]
	v_div_fmas_f32 v161, v183, v161, v189
	v_div_fixup_f32 v189, v161, v197, 1.0
	v_fma_f32 v161, -v231, v213, 1.0
	v_fmac_f32_e32 v213, v161, v213
	v_div_scale_f32 v161, vcc, 1.0, v198, 1.0
	v_mul_f32_e32 v183, v161, v213
	v_div_scale_f32 v197, s[0:1], v199, v199, 1.0
	v_div_fixup_f32 v188, v188, v196, 1.0
	v_fma_f32 v196, -v231, v183, v161
	v_rcp_f32_e32 v203, v197
	v_fmac_f32_e32 v183, v196, v213
	v_fma_f32 v161, -v231, v183, v161
	v_div_fmas_f32 v161, v161, v213, v183
	v_div_fixup_f32 v196, v161, v198, 1.0
	v_fma_f32 v161, -v197, v203, 1.0
	v_fmac_f32_e32 v203, v161, v203
	v_div_scale_f32 v161, vcc, 1.0, v199, 1.0
	v_mul_f32_e32 v183, v161, v203
	v_fma_f32 v198, -v197, v183, v161
	v_fmac_f32_e32 v183, v198, v203
	v_fma_f32 v161, -v197, v183, v161
	v_div_fmas_f32 v161, v161, v203, v183
	s_waitcnt vmcnt(1)
	v_div_scale_f32 v198, s[0:1], v204, v204, 1.0
	v_rcp_f32_e32 v212, v198
	v_div_fixup_f32 v197, v161, v199, 1.0
	v_lshlrev_b32_e32 v246, 16, v227
	v_and_b32_e32 v247, 0xffff0000, v227
	v_fma_f32 v161, -v198, v212, 1.0
	v_fmac_f32_e32 v212, v161, v212
	v_div_scale_f32 v161, vcc, 1.0, v204, 1.0
	v_mul_f32_e32 v183, v161, v212
	v_fma_f32 v199, -v198, v183, v161
	v_fmac_f32_e32 v183, v199, v212
	v_div_scale_f32 v199, s[0:1], v205, v205, 1.0
	v_rcp_f32_e32 v203, v199
	v_fma_f32 v161, -v198, v183, v161
	v_div_fmas_f32 v161, v161, v212, v183
	v_div_fixup_f32 v198, v161, v204, 1.0
	v_fma_f32 v161, -v199, v203, 1.0
	v_fmac_f32_e32 v203, v161, v203
	v_div_scale_f32 v161, vcc, 1.0, v205, 1.0
	v_mul_f32_e32 v183, v161, v203
	v_fma_f32 v204, -v199, v183, v161
	v_fmac_f32_e32 v183, v204, v203
	v_div_scale_f32 v204, s[0:1], v206, v206, 1.0
	v_rcp_f32_e32 v212, v204
	v_fma_f32 v161, -v199, v183, v161
	v_div_fmas_f32 v161, v161, v203, v183
	v_div_fixup_f32 v199, v161, v205, 1.0
	v_fma_f32 v161, -v204, v212, 1.0
	v_fmac_f32_e32 v212, v161, v212
	v_div_scale_f32 v161, vcc, 1.0, v206, 1.0
	v_mul_f32_e32 v183, v161, v212
	v_fma_f32 v203, -v204, v183, v161
	v_fmac_f32_e32 v183, v203, v212
	v_div_scale_f32 v203, s[0:1], v207, v207, 1.0
	v_rcp_f32_e32 v205, v203
	v_fma_f32 v161, -v204, v183, v161
	v_div_fmas_f32 v161, v161, v212, v183
	v_div_fixup_f32 v204, v161, v206, 1.0
	v_fma_f32 v161, -v203, v205, 1.0
	v_fmac_f32_e32 v205, v161, v205
	v_div_scale_f32 v161, vcc, 1.0, v207, 1.0
	v_mul_f32_e32 v183, v161, v205
	v_fma_f32 v206, -v203, v183, v161
	v_fmac_f32_e32 v183, v206, v205
	v_fma_f32 v161, -v203, v183, v161
	s_waitcnt vmcnt(0)
	v_div_scale_f32 v203, s[0:1], v240, v240, 1.0
	v_rcp_f32_e32 v206, v203
	v_div_fmas_f32 v161, v161, v205, v183
	v_div_fixup_f32 v205, v161, v207, 1.0
	v_lshlrev_b32_e32 v244, 16, v226
	v_fma_f32 v161, -v203, v206, 1.0
	v_fmac_f32_e32 v206, v161, v206
	v_div_scale_f32 v161, vcc, 1.0, v240, 1.0
	v_mul_f32_e32 v183, v161, v206
	v_fma_f32 v207, -v203, v183, v161
	v_fmac_f32_e32 v183, v207, v206
	v_fma_f32 v161, -v203, v183, v161
	v_div_scale_f32 v203, s[0:1], v241, v241, 1.0
	v_rcp_f32_e32 v207, v203
	v_div_fmas_f32 v161, v161, v206, v183
	v_div_fixup_f32 v206, v161, v240, 1.0
	v_and_b32_e32 v245, 0xffff0000, v226
	v_fma_f32 v161, -v203, v207, 1.0
	v_fmac_f32_e32 v207, v161, v207
	v_div_scale_f32 v161, vcc, 1.0, v241, 1.0
	v_mul_f32_e32 v183, v161, v207
	v_fma_f32 v212, -v203, v183, v161
	v_fmac_f32_e32 v183, v212, v207
	v_fma_f32 v161, -v203, v183, v161
	v_div_scale_f32 v203, s[0:1], v242, v242, 1.0
	v_rcp_f32_e32 v212, v203
	v_div_fmas_f32 v161, v161, v207, v183
	v_div_fixup_f32 v207, v161, v241, 1.0
	v_add_u32_e32 v226, s16, v151
	v_fma_f32 v161, -v203, v212, 1.0
	v_fmac_f32_e32 v212, v161, v212
	v_div_scale_f32 v161, vcc, 1.0, v242, 1.0
	v_mul_f32_e32 v183, v161, v212
	v_fma_f32 v213, -v203, v183, v161
	v_fmac_f32_e32 v183, v213, v212
	v_fma_f32 v161, -v203, v183, v161
	v_div_scale_f32 v203, s[0:1], v243, v243, 1.0
	v_rcp_f32_e32 v213, v203
	v_div_fmas_f32 v161, v161, v212, v183
	v_div_fixup_f32 v212, v161, v242, 1.0
	v_ashrrev_i32_e32 v227, 31, v226
	v_fma_f32 v161, -v203, v213, 1.0
	v_fmac_f32_e32 v213, v161, v213
	v_div_scale_f32 v161, vcc, 1.0, v243, 1.0
	v_mul_f32_e32 v183, v161, v213
	v_fma_f32 v219, -v203, v183, v161
	v_fmac_f32_e32 v183, v219, v213
	v_fma_f32 v161, -v203, v183, v161
	v_div_fmas_f32 v161, v161, v213, v183
	v_div_fixup_f32 v213, v161, v243, 1.0
	v_lshl_add_u32 v161, v151, 3, 0
	v_add_u32_e32 v161, 0x2000, v161
	ds_read2_b64 v[240:243], v161 offset1:16
	v_cmp_ne_u32_e32 vcc, 0, v171
	v_pk_mul_f32 v[244:245], v[230:231], v[244:245] op_sel_hi:[0,1]
	s_waitcnt lgkmcnt(0)
	v_pk_mul_f32 v[248:249], v[124:125], v[240:241] op_sel:[0,1]
	v_pk_mul_f32 v[250:251], v[126:127], v[240:241] op_sel:[0,1]
	global_load_dwordx4 v[124:127], v[238:239], off offset:576
	v_pk_mul_f32 v[238:239], v[230:231], v[246:247] op_sel_hi:[0,1]
	v_pk_mul_f32 v[246:247], v[138:139], v[250:251]
	v_pk_mul_f32 v[248:249], v[136:137], v[248:249]
	v_pk_fma_f32 v[238:239], v[238:239], v[192:193], v[246:247]
	v_pk_fma_f32 v[244:245], v[244:245], v[190:191], v[248:249]
	v_cndmask_b32_e32 v247, v239, v141, vcc
	v_cndmask_b32_e32 v246, v238, v141, vcc
	v_lshlrev_b64 v[238:239], 12, v[226:227]
	v_lshl_add_u64 v[238:239], s[64:65], 0, v[238:239]
	v_cndmask_b32_e32 v245, v245, v141, vcc
	v_cndmask_b32_e32 v244, v244, v141, vcc
	v_lshl_add_u64 v[238:239], v[238:239], 0, v[172:173]
	global_store_dwordx4 v[238:239], v[244:247], off sc1
	v_pk_mul_f32 v[120:121], v[120:121], v[240:241] op_sel:[0,1]
	v_pk_mul_f32 v[122:123], v[122:123], v[240:241] op_sel:[0,1]
	v_lshlrev_b32_e32 v244, 16, v236
	v_and_b32_e32 v245, 0xffff0000, v236
	v_lshlrev_b32_e32 v236, 16, v237
	v_and_b32_e32 v237, 0xffff0000, v237
	v_pk_mul_f32 v[236:237], v[230:231], v[236:237] op_sel_hi:[0,1]
	v_pk_mul_f32 v[244:245], v[230:231], v[244:245] op_sel_hi:[0,1]
	v_pk_mul_f32 v[122:123], v[134:135], v[122:123]
	v_pk_mul_f32 v[120:121], v[132:133], v[120:121]
	v_pk_fma_f32 v[122:123], v[236:237], v[196:197], v[122:123]
	v_pk_fma_f32 v[120:121], v[244:245], v[188:189], v[120:121]
	v_cndmask_b32_e32 v123, v123, v141, vcc
	v_cndmask_b32_e32 v122, v122, v141, vcc
	v_cndmask_b32_e32 v121, v121, v141, vcc
	v_cndmask_b32_e32 v120, v120, v141, vcc
	global_store_dwordx4 v[238:239], v[120:123], off offset:64 sc1
	v_pk_mul_f32 v[118:119], v[118:119], v[240:241] op_sel:[0,1]
	v_pk_mul_f32 v[116:117], v[116:117], v[240:241] op_sel:[0,1]
	v_lshlrev_b32_e32 v120, 16, v234
	v_and_b32_e32 v121, 0xffff0000, v234
	v_lshlrev_b32_e32 v122, 16, v235
	v_and_b32_e32 v123, 0xffff0000, v235
	v_pk_mul_f32 v[120:121], v[230:231], v[120:121] op_sel_hi:[0,1]
	v_pk_mul_f32 v[122:123], v[230:231], v[122:123] op_sel_hi:[0,1]
	v_pk_mul_f32 v[122:123], v[122:123], v[204:205]
	v_pk_mul_f32 v[120:121], v[120:121], v[198:199]
	v_pk_fma_f32 v[118:119], v[130:131], v[118:119], v[122:123]
	v_pk_fma_f32 v[116:117], v[128:129], v[116:117], v[120:121]
	v_cndmask_b32_e32 v119, v119, v141, vcc
	v_cndmask_b32_e32 v118, v118, v141, vcc
	v_cndmask_b32_e32 v117, v117, v141, vcc
	v_cndmask_b32_e32 v116, v116, v141, vcc
	global_store_dwordx4 v[238:239], v[116:119], off offset:512 sc1
	v_pk_mul_f32 v[110:111], v[110:111], v[240:241] op_sel:[0,1]
	v_pk_mul_f32 v[108:109], v[108:109], v[240:241] op_sel:[0,1]
	v_lshlrev_b32_e32 v116, 16, v232
	v_and_b32_e32 v117, 0xffff0000, v232
	v_lshlrev_b32_e32 v118, 16, v233
	v_and_b32_e32 v119, 0xffff0000, v233
	v_pk_mul_f32 v[116:117], v[230:231], v[116:117] op_sel_hi:[0,1]
	v_pk_mul_f32 v[118:119], v[230:231], v[118:119] op_sel_hi:[0,1]
	v_pk_mul_f32 v[118:119], v[118:119], v[212:213]
	v_pk_mul_f32 v[116:117], v[116:117], v[206:207]
	v_pk_mul_f32 v[112:113], v[112:113], v[242:243] op_sel:[0,1]
	v_pk_mul_f32 v[114:115], v[114:115], v[242:243] op_sel:[0,1]
	v_pk_mul_f32 v[112:113], v[136:137], v[112:113]
	v_pk_mul_f32 v[114:115], v[138:139], v[114:115]
	v_pk_mul_f32 v[104:105], v[104:105], v[242:243] op_sel:[0,1]
	v_pk_mul_f32 v[106:107], v[106:107], v[242:243] op_sel:[0,1]
	v_pk_mul_f32 v[104:105], v[132:133], v[104:105]
	v_pk_mul_f32 v[106:107], v[134:135], v[106:107]
	v_pk_mul_f32 v[100:101], v[100:101], v[242:243] op_sel:[0,1]
	v_pk_mul_f32 v[102:103], v[102:103], v[242:243] op_sel:[0,1]
	v_pk_mul_f32 v[100:101], v[128:129], v[100:101]
	v_pk_mul_f32 v[102:103], v[130:131], v[102:103]
	v_pk_mul_f32 v[92:93], v[92:93], v[242:243] op_sel:[0,1]
	v_pk_mul_f32 v[94:95], v[94:95], v[242:243] op_sel:[0,1]
	s_waitcnt vmcnt(3)
	v_pk_fma_f32 v[108:109], v[124:125], v[108:109], v[116:117]
	v_pk_fma_f32 v[110:111], v[126:127], v[110:111], v[118:119]
	v_cndmask_b32_e32 v109, v109, v141, vcc
	v_cndmask_b32_e32 v111, v111, v141, vcc
	v_cndmask_b32_e32 v110, v110, v141, vcc
	v_cndmask_b32_e32 v108, v108, v141, vcc
	global_store_dwordx4 v[238:239], v[108:111], off offset:576 sc1
	v_add_u32_e32 v116, 16, v226
	v_ashrrev_i32_e32 v117, 31, v116
	v_lshlrev_b32_e32 v108, 16, v228
	v_and_b32_e32 v109, 0xffff0000, v228
	v_lshlrev_b32_e32 v110, 16, v229
	v_and_b32_e32 v111, 0xffff0000, v229
	v_pk_mul_f32 v[108:109], v[218:219], v[108:109] op_sel_hi:[0,1]
	v_pk_mul_f32 v[110:111], v[218:219], v[110:111] op_sel_hi:[0,1]
	v_pk_fma_f32 v[108:109], v[108:109], v[190:191], v[112:113]
	v_lshlrev_b64 v[112:113], 12, v[116:117]
	v_pk_fma_f32 v[110:111], v[110:111], v[192:193], v[114:115]
	v_lshl_add_u64 v[112:113], s[64:65], 0, v[112:113]
	v_cndmask_b32_e32 v111, v111, v141, vcc
	v_cndmask_b32_e32 v110, v110, v141, vcc
	v_cndmask_b32_e32 v109, v109, v141, vcc
	v_cndmask_b32_e32 v108, v108, v141, vcc
	v_lshl_add_u64 v[112:113], v[112:113], 0, v[172:173]
	global_store_dwordx4 v[112:113], v[108:111], off sc1
	v_pk_mul_f32 v[94:95], v[126:127], v[94:95]
	v_pk_mul_f32 v[92:93], v[124:125], v[92:93]
	v_lshlrev_b32_e32 v108, 16, v224
	v_and_b32_e32 v109, 0xffff0000, v224
	v_lshlrev_b32_e32 v110, 16, v225
	v_and_b32_e32 v111, 0xffff0000, v225
	v_pk_mul_f32 v[110:111], v[218:219], v[110:111] op_sel_hi:[0,1]
	v_pk_mul_f32 v[108:109], v[218:219], v[108:109] op_sel_hi:[0,1]
	v_pk_fma_f32 v[104:105], v[108:109], v[188:189], v[104:105]
	v_pk_fma_f32 v[106:107], v[110:111], v[196:197], v[106:107]
	v_cndmask_b32_e32 v105, v105, v141, vcc
	v_cndmask_b32_e32 v107, v107, v141, vcc
	v_cndmask_b32_e32 v106, v106, v141, vcc
	v_cndmask_b32_e32 v104, v104, v141, vcc
	global_store_dwordx4 v[112:113], v[104:107], off offset:64 sc1
	s_nop 1
	v_lshlrev_b32_e32 v104, 16, v222
	v_and_b32_e32 v105, 0xffff0000, v222
	v_lshlrev_b32_e32 v106, 16, v223
	v_and_b32_e32 v107, 0xffff0000, v223
	v_pk_mul_f32 v[106:107], v[218:219], v[106:107] op_sel_hi:[0,1]
	v_pk_mul_f32 v[104:105], v[218:219], v[104:105] op_sel_hi:[0,1]
	v_pk_fma_f32 v[100:101], v[104:105], v[198:199], v[100:101]
	v_pk_fma_f32 v[102:103], v[106:107], v[204:205], v[102:103]
	v_cndmask_b32_e32 v101, v101, v141, vcc
	v_cndmask_b32_e32 v103, v103, v141, vcc
	v_cndmask_b32_e32 v102, v102, v141, vcc
	v_cndmask_b32_e32 v100, v100, v141, vcc
	global_store_dwordx4 v[112:113], v[100:103], off offset:512 sc1
	v_lshlrev_b32_e32 v104, 16, v217
	v_and_b32_e32 v105, 0xffff0000, v217
	v_lshlrev_b32_e32 v100, 16, v220
	v_and_b32_e32 v101, 0xffff0000, v220
	v_lshlrev_b32_e32 v102, 16, v221
	v_and_b32_e32 v103, 0xffff0000, v221
	v_pk_mul_f32 v[102:103], v[218:219], v[102:103] op_sel_hi:[0,1]
	v_pk_mul_f32 v[100:101], v[218:219], v[100:101] op_sel_hi:[0,1]
	v_pk_fma_f32 v[92:93], v[100:101], v[206:207], v[92:93]
	v_pk_fma_f32 v[94:95], v[102:103], v[212:213], v[94:95]
	v_cndmask_b32_e32 v93, v93, v141, vcc
	v_cndmask_b32_e32 v95, v95, v141, vcc
	v_cndmask_b32_e32 v94, v94, v141, vcc
	v_cndmask_b32_e32 v92, v92, v141, vcc
	global_store_dwordx4 v[112:113], v[92:95], off offset:576 sc1
	ds_read2_b64 v[92:95], v161 offset0:32 offset1:48
	v_add_u32_e32 v100, 32, v226
	v_ashrrev_i32_e32 v101, 31, v100
	v_lshlrev_b32_e32 v102, 16, v216
	v_and_b32_e32 v103, 0xffff0000, v216
	s_waitcnt lgkmcnt(0)
	v_pk_mul_f32 v[96:97], v[96:97], v[92:93] op_sel:[0,1]
	v_pk_mul_f32 v[98:99], v[98:99], v[92:93] op_sel:[0,1]
	v_pk_mul_f32 v[104:105], v[202:203], v[104:105] op_sel_hi:[0,1]
	v_pk_mul_f32 v[102:103], v[202:203], v[102:103] op_sel_hi:[0,1]
	v_pk_mul_f32 v[98:99], v[138:139], v[98:99]
	v_pk_mul_f32 v[96:97], v[136:137], v[96:97]
	v_lshlrev_b64 v[100:101], 12, v[100:101]
	v_pk_fma_f32 v[96:97], v[102:103], v[190:191], v[96:97]
	v_pk_fma_f32 v[98:99], v[104:105], v[192:193], v[98:99]
	v_lshl_add_u64 v[100:101], s[64:65], 0, v[100:101]
	v_cndmask_b32_e32 v99, v99, v141, vcc
	v_cndmask_b32_e32 v98, v98, v141, vcc
	v_cndmask_b32_e32 v97, v97, v141, vcc
	v_cndmask_b32_e32 v96, v96, v141, vcc
	v_lshl_add_u64 v[100:101], v[100:101], 0, v[172:173]
	global_store_dwordx4 v[100:101], v[96:99], off sc1
	v_pk_mul_f32 v[88:89], v[88:89], v[92:93] op_sel:[0,1]
	v_pk_mul_f32 v[90:91], v[90:91], v[92:93] op_sel:[0,1]
	v_lshlrev_b32_e32 v96, 16, v214
	v_and_b32_e32 v97, 0xffff0000, v214
	v_lshlrev_b32_e32 v98, 16, v215
	v_and_b32_e32 v99, 0xffff0000, v215
	v_pk_mul_f32 v[98:99], v[202:203], v[98:99] op_sel_hi:[0,1]
	v_pk_mul_f32 v[96:97], v[202:203], v[96:97] op_sel_hi:[0,1]
	v_pk_mul_f32 v[90:91], v[134:135], v[90:91]
	v_pk_mul_f32 v[88:89], v[132:133], v[88:89]
	v_pk_fma_f32 v[90:91], v[98:99], v[196:197], v[90:91]
	v_pk_fma_f32 v[88:89], v[96:97], v[188:189], v[88:89]
	v_cndmask_b32_e32 v91, v91, v141, vcc
	v_cndmask_b32_e32 v90, v90, v141, vcc
	v_cndmask_b32_e32 v89, v89, v141, vcc
	v_cndmask_b32_e32 v88, v88, v141, vcc
	global_store_dwordx4 v[100:101], v[88:91], off offset:64 sc1
	v_pk_mul_f32 v[84:85], v[84:85], v[92:93] op_sel:[0,1]
	v_pk_mul_f32 v[86:87], v[86:87], v[92:93] op_sel:[0,1]
	v_lshlrev_b32_e32 v88, 16, v210
	v_and_b32_e32 v89, 0xffff0000, v210
	v_lshlrev_b32_e32 v90, 16, v211
	v_and_b32_e32 v91, 0xffff0000, v211
	v_pk_mul_f32 v[90:91], v[202:203], v[90:91] op_sel_hi:[0,1]
	v_pk_mul_f32 v[88:89], v[202:203], v[88:89] op_sel_hi:[0,1]
	v_pk_mul_f32 v[86:87], v[130:131], v[86:87]
	v_pk_mul_f32 v[84:85], v[128:129], v[84:85]
	v_pk_fma_f32 v[86:87], v[90:91], v[204:205], v[86:87]
	v_pk_fma_f32 v[84:85], v[88:89], v[198:199], v[84:85]
	v_cndmask_b32_e32 v87, v87, v141, vcc
	v_cndmask_b32_e32 v86, v86, v141, vcc
	v_cndmask_b32_e32 v85, v85, v141, vcc
	v_cndmask_b32_e32 v84, v84, v141, vcc
	global_store_dwordx4 v[100:101], v[84:87], off offset:512 sc1
	v_pk_mul_f32 v[76:77], v[76:77], v[92:93] op_sel:[0,1]
	v_pk_mul_f32 v[78:79], v[78:79], v[92:93] op_sel:[0,1]
	v_lshlrev_b32_e32 v84, 16, v208
	v_and_b32_e32 v85, 0xffff0000, v208
	v_lshlrev_b32_e32 v86, 16, v209
	v_and_b32_e32 v87, 0xffff0000, v209
	v_pk_mul_f32 v[86:87], v[202:203], v[86:87] op_sel_hi:[0,1]
	v_pk_mul_f32 v[84:85], v[202:203], v[84:85] op_sel_hi:[0,1]
	v_pk_mul_f32 v[78:79], v[126:127], v[78:79]
	v_pk_mul_f32 v[76:77], v[124:125], v[76:77]
	v_pk_fma_f32 v[78:79], v[86:87], v[212:213], v[78:79]
	v_pk_fma_f32 v[76:77], v[84:85], v[206:207], v[76:77]
	v_cndmask_b32_e32 v79, v79, v141, vcc
	v_cndmask_b32_e32 v78, v78, v141, vcc
	v_cndmask_b32_e32 v77, v77, v141, vcc
	v_cndmask_b32_e32 v76, v76, v141, vcc
	global_store_dwordx4 v[100:101], v[76:79], off offset:576 sc1
	v_add_u32_e32 v84, 48, v226
	v_pk_mul_f32 v[80:81], v[80:81], v[94:95] op_sel:[0,1]
	v_lshlrev_b32_e32 v76, 16, v200
	v_and_b32_e32 v77, 0xffff0000, v200
	v_ashrrev_i32_e32 v85, 31, v84
	v_lshlrev_b32_e32 v78, 16, v201
	v_and_b32_e32 v79, 0xffff0000, v201
	v_pk_mul_f32 v[76:77], v[182:183], v[76:77] op_sel_hi:[0,1]
	v_pk_mul_f32 v[82:83], v[82:83], v[94:95] op_sel:[0,1]
	v_pk_mul_f32 v[80:81], v[136:137], v[80:81]
	v_pk_mul_f32 v[78:79], v[182:183], v[78:79] op_sel_hi:[0,1]
	v_pk_mul_f32 v[82:83], v[138:139], v[82:83]
	v_pk_fma_f32 v[76:77], v[76:77], v[190:191], v[80:81]
	v_lshlrev_b64 v[80:81], 12, v[84:85]
	v_pk_fma_f32 v[78:79], v[78:79], v[192:193], v[82:83]
	v_lshl_add_u64 v[80:81], s[64:65], 0, v[80:81]
	v_cndmask_b32_e32 v79, v79, v141, vcc
	v_cndmask_b32_e32 v78, v78, v141, vcc
	v_cndmask_b32_e32 v77, v77, v141, vcc
	v_cndmask_b32_e32 v76, v76, v141, vcc
	v_lshl_add_u64 v[80:81], v[80:81], 0, v[172:173]
	global_store_dwordx4 v[80:81], v[76:79], off sc1
	v_pk_mul_f32 v[72:73], v[72:73], v[94:95] op_sel:[0,1]
	v_pk_mul_f32 v[74:75], v[74:75], v[94:95] op_sel:[0,1]
	v_lshlrev_b32_e32 v76, 16, v194
	v_and_b32_e32 v77, 0xffff0000, v194
	v_lshlrev_b32_e32 v78, 16, v195
	v_and_b32_e32 v79, 0xffff0000, v195
	v_pk_mul_f32 v[78:79], v[182:183], v[78:79] op_sel_hi:[0,1]
	v_pk_mul_f32 v[76:77], v[182:183], v[76:77] op_sel_hi:[0,1]
	v_pk_mul_f32 v[74:75], v[134:135], v[74:75]
	v_pk_mul_f32 v[72:73], v[132:133], v[72:73]
	v_pk_fma_f32 v[74:75], v[78:79], v[196:197], v[74:75]
	v_pk_fma_f32 v[72:73], v[76:77], v[188:189], v[72:73]
	v_cndmask_b32_e32 v75, v75, v141, vcc
	v_cndmask_b32_e32 v74, v74, v141, vcc
	v_cndmask_b32_e32 v73, v73, v141, vcc
	v_cndmask_b32_e32 v72, v72, v141, vcc
	global_store_dwordx4 v[80:81], v[72:75], off offset:64 sc1
	v_pk_mul_f32 v[68:69], v[68:69], v[94:95] op_sel:[0,1]
	v_pk_mul_f32 v[70:71], v[70:71], v[94:95] op_sel:[0,1]
	v_lshlrev_b32_e32 v72, 16, v186
	v_and_b32_e32 v73, 0xffff0000, v186
	v_lshlrev_b32_e32 v74, 16, v187
	v_and_b32_e32 v75, 0xffff0000, v187
	v_pk_mul_f32 v[74:75], v[182:183], v[74:75] op_sel_hi:[0,1]
	v_pk_mul_f32 v[72:73], v[182:183], v[72:73] op_sel_hi:[0,1]
	v_pk_mul_f32 v[70:71], v[130:131], v[70:71]
	v_pk_mul_f32 v[68:69], v[128:129], v[68:69]
	v_pk_fma_f32 v[70:71], v[74:75], v[204:205], v[70:71]
	v_pk_fma_f32 v[68:69], v[72:73], v[198:199], v[68:69]
	v_cndmask_b32_e32 v71, v71, v141, vcc
	v_cndmask_b32_e32 v70, v70, v141, vcc
	v_cndmask_b32_e32 v69, v69, v141, vcc
	v_cndmask_b32_e32 v68, v68, v141, vcc
	global_store_dwordx4 v[80:81], v[68:71], off offset:512 sc1
	v_pk_mul_f32 v[64:65], v[64:65], v[94:95] op_sel:[0,1]
	v_pk_mul_f32 v[66:67], v[66:67], v[94:95] op_sel:[0,1]
	v_lshlrev_b32_e32 v68, 16, v184
	v_and_b32_e32 v69, 0xffff0000, v184
	v_lshlrev_b32_e32 v70, 16, v185
	v_and_b32_e32 v71, 0xffff0000, v185
	v_pk_mul_f32 v[70:71], v[182:183], v[70:71] op_sel_hi:[0,1]
	v_pk_mul_f32 v[68:69], v[182:183], v[68:69] op_sel_hi:[0,1]
	v_pk_mul_f32 v[66:67], v[126:127], v[66:67]
	v_pk_mul_f32 v[64:65], v[124:125], v[64:65]
	v_pk_fma_f32 v[66:67], v[70:71], v[212:213], v[66:67]
	v_pk_fma_f32 v[64:65], v[68:69], v[206:207], v[64:65]
	v_cndmask_b32_e32 v67, v67, v141, vcc
	v_cndmask_b32_e32 v66, v66, v141, vcc
	v_cndmask_b32_e32 v65, v65, v141, vcc
	v_cndmask_b32_e32 v64, v64, v141, vcc
	global_store_dwordx4 v[80:81], v[64:67], off offset:576 sc1
	ds_read2_b64 v[64:67], v161 offset0:128 offset1:144
	v_add_u32_e32 v68, 0x80, v226
	v_ashrrev_i32_e32 v69, 31, v68
	v_lshlrev_b32_e32 v70, 16, v180
	v_and_b32_e32 v71, 0xffff0000, v180
	v_lshlrev_b32_e32 v72, 16, v181
	v_and_b32_e32 v73, 0xffff0000, v181
	s_waitcnt lgkmcnt(0)
	v_pk_mul_f32 v[60:61], v[60:61], v[64:65] op_sel:[0,1]
	v_pk_mul_f32 v[62:63], v[62:63], v[64:65] op_sel:[0,1]
	v_pk_mul_f32 v[72:73], v[170:171], v[72:73] op_sel_hi:[0,1]
	v_pk_mul_f32 v[70:71], v[170:171], v[70:71] op_sel_hi:[0,1]
	v_pk_mul_f32 v[62:63], v[138:139], v[62:63]
	v_pk_mul_f32 v[60:61], v[136:137], v[60:61]
	v_lshlrev_b64 v[68:69], 12, v[68:69]
	v_pk_fma_f32 v[60:61], v[70:71], v[190:191], v[60:61]
	v_pk_fma_f32 v[62:63], v[72:73], v[192:193], v[62:63]
	v_lshl_add_u64 v[68:69], s[64:65], 0, v[68:69]
	v_cndmask_b32_e32 v63, v63, v141, vcc
	v_cndmask_b32_e32 v62, v62, v141, vcc
	v_cndmask_b32_e32 v61, v61, v141, vcc
	v_cndmask_b32_e32 v60, v60, v141, vcc
	v_lshl_add_u64 v[68:69], v[68:69], 0, v[172:173]
	global_store_dwordx4 v[68:69], v[60:63], off sc1
	v_pk_mul_f32 v[56:57], v[56:57], v[64:65] op_sel:[0,1]
	v_pk_mul_f32 v[58:59], v[58:59], v[64:65] op_sel:[0,1]
	v_lshlrev_b32_e32 v60, 16, v178
	v_and_b32_e32 v61, 0xffff0000, v178
	v_lshlrev_b32_e32 v62, 16, v179
	v_and_b32_e32 v63, 0xffff0000, v179
	v_pk_mul_f32 v[62:63], v[170:171], v[62:63] op_sel_hi:[0,1]
	v_pk_mul_f32 v[60:61], v[170:171], v[60:61] op_sel_hi:[0,1]
	v_pk_mul_f32 v[58:59], v[134:135], v[58:59]
	v_pk_mul_f32 v[56:57], v[132:133], v[56:57]
	v_pk_fma_f32 v[58:59], v[62:63], v[196:197], v[58:59]
	v_pk_fma_f32 v[56:57], v[60:61], v[188:189], v[56:57]
	v_cndmask_b32_e32 v59, v59, v141, vcc
	v_cndmask_b32_e32 v58, v58, v141, vcc
	v_cndmask_b32_e32 v57, v57, v141, vcc
	v_cndmask_b32_e32 v56, v56, v141, vcc
	global_store_dwordx4 v[68:69], v[56:59], off offset:64 sc1
	v_pk_mul_f32 v[52:53], v[52:53], v[64:65] op_sel:[0,1]
	v_pk_mul_f32 v[54:55], v[54:55], v[64:65] op_sel:[0,1]
	v_lshlrev_b32_e32 v56, 16, v176
	v_and_b32_e32 v57, 0xffff0000, v176
	v_lshlrev_b32_e32 v58, 16, v177
	v_and_b32_e32 v59, 0xffff0000, v177
	v_pk_mul_f32 v[58:59], v[170:171], v[58:59] op_sel_hi:[0,1]
	v_pk_mul_f32 v[56:57], v[170:171], v[56:57] op_sel_hi:[0,1]
	v_pk_mul_f32 v[54:55], v[130:131], v[54:55]
	v_pk_mul_f32 v[52:53], v[128:129], v[52:53]
	v_pk_fma_f32 v[54:55], v[58:59], v[204:205], v[54:55]
	v_pk_fma_f32 v[52:53], v[56:57], v[198:199], v[52:53]
	v_cndmask_b32_e32 v55, v55, v141, vcc
	v_cndmask_b32_e32 v54, v54, v141, vcc
	v_cndmask_b32_e32 v53, v53, v141, vcc
	v_cndmask_b32_e32 v52, v52, v141, vcc
	global_store_dwordx4 v[68:69], v[52:55], off offset:512 sc1
	v_pk_mul_f32 v[44:45], v[44:45], v[64:65] op_sel:[0,1]
	v_pk_mul_f32 v[46:47], v[46:47], v[64:65] op_sel:[0,1]
	v_lshlrev_b32_e32 v52, 16, v174
	v_and_b32_e32 v53, 0xffff0000, v174
	v_lshlrev_b32_e32 v54, 16, v175
	v_and_b32_e32 v55, 0xffff0000, v175
	v_pk_mul_f32 v[54:55], v[170:171], v[54:55] op_sel_hi:[0,1]
	v_pk_mul_f32 v[52:53], v[170:171], v[52:53] op_sel_hi:[0,1]
	v_pk_mul_f32 v[46:47], v[126:127], v[46:47]
	v_pk_mul_f32 v[44:45], v[124:125], v[44:45]
	v_pk_fma_f32 v[46:47], v[54:55], v[212:213], v[46:47]
	v_pk_fma_f32 v[44:45], v[52:53], v[206:207], v[44:45]
	v_cndmask_b32_e32 v47, v47, v141, vcc
	v_cndmask_b32_e32 v46, v46, v141, vcc
	v_cndmask_b32_e32 v45, v45, v141, vcc
	v_cndmask_b32_e32 v44, v44, v141, vcc
	global_store_dwordx4 v[68:69], v[44:47], off offset:576 sc1
	v_add_u32_e32 v52, 0x90, v226
	v_pk_mul_f32 v[48:49], v[48:49], v[66:67] op_sel:[0,1]
	v_lshlrev_b32_e32 v44, 16, v168
	v_and_b32_e32 v45, 0xffff0000, v168
	v_ashrrev_i32_e32 v53, 31, v52
	v_lshlrev_b32_e32 v46, 16, v169
	v_and_b32_e32 v47, 0xffff0000, v169
	v_pk_mul_f32 v[44:45], v[160:161], v[44:45] op_sel_hi:[0,1]
	v_pk_mul_f32 v[50:51], v[50:51], v[66:67] op_sel:[0,1]
	v_pk_mul_f32 v[48:49], v[136:137], v[48:49]
	v_pk_mul_f32 v[46:47], v[160:161], v[46:47] op_sel_hi:[0,1]
	v_pk_mul_f32 v[50:51], v[138:139], v[50:51]
	v_pk_fma_f32 v[44:45], v[44:45], v[190:191], v[48:49]
	v_lshlrev_b64 v[48:49], 12, v[52:53]
	v_pk_fma_f32 v[46:47], v[46:47], v[192:193], v[50:51]
	v_lshl_add_u64 v[48:49], s[64:65], 0, v[48:49]
	v_cndmask_b32_e32 v47, v47, v141, vcc
	v_cndmask_b32_e32 v46, v46, v141, vcc
	v_cndmask_b32_e32 v45, v45, v141, vcc
	v_cndmask_b32_e32 v44, v44, v141, vcc
	v_lshl_add_u64 v[48:49], v[48:49], 0, v[172:173]
	global_store_dwordx4 v[48:49], v[44:47], off sc1
	v_pk_mul_f32 v[40:41], v[40:41], v[66:67] op_sel:[0,1]
	v_pk_mul_f32 v[42:43], v[42:43], v[66:67] op_sel:[0,1]
	v_lshlrev_b32_e32 v44, 16, v166
	v_and_b32_e32 v45, 0xffff0000, v166
	v_lshlrev_b32_e32 v46, 16, v167
	v_and_b32_e32 v47, 0xffff0000, v167
	v_pk_mul_f32 v[46:47], v[160:161], v[46:47] op_sel_hi:[0,1]
	v_pk_mul_f32 v[44:45], v[160:161], v[44:45] op_sel_hi:[0,1]
	v_pk_mul_f32 v[42:43], v[134:135], v[42:43]
	v_pk_mul_f32 v[40:41], v[132:133], v[40:41]
	v_pk_fma_f32 v[42:43], v[46:47], v[196:197], v[42:43]
	v_pk_fma_f32 v[40:41], v[44:45], v[188:189], v[40:41]
	v_cndmask_b32_e32 v43, v43, v141, vcc
	v_cndmask_b32_e32 v42, v42, v141, vcc
	v_cndmask_b32_e32 v41, v41, v141, vcc
	v_cndmask_b32_e32 v40, v40, v141, vcc
	global_store_dwordx4 v[48:49], v[40:43], off offset:64 sc1
	v_pk_mul_f32 v[36:37], v[36:37], v[66:67] op_sel:[0,1]
	v_pk_mul_f32 v[38:39], v[38:39], v[66:67] op_sel:[0,1]
	v_lshlrev_b32_e32 v40, 16, v164
	v_and_b32_e32 v41, 0xffff0000, v164
	v_lshlrev_b32_e32 v42, 16, v165
	v_and_b32_e32 v43, 0xffff0000, v165
	v_pk_mul_f32 v[42:43], v[160:161], v[42:43] op_sel_hi:[0,1]
	v_pk_mul_f32 v[40:41], v[160:161], v[40:41] op_sel_hi:[0,1]
	v_pk_mul_f32 v[38:39], v[130:131], v[38:39]
	v_pk_mul_f32 v[36:37], v[128:129], v[36:37]
	v_pk_fma_f32 v[38:39], v[42:43], v[204:205], v[38:39]
	v_pk_fma_f32 v[36:37], v[40:41], v[198:199], v[36:37]
	v_cndmask_b32_e32 v39, v39, v141, vcc
	v_cndmask_b32_e32 v38, v38, v141, vcc
	v_cndmask_b32_e32 v37, v37, v141, vcc
	v_cndmask_b32_e32 v36, v36, v141, vcc
	global_store_dwordx4 v[48:49], v[36:39], off offset:512 sc1
	v_pk_mul_f32 v[28:29], v[28:29], v[66:67] op_sel:[0,1]
	v_pk_mul_f32 v[30:31], v[30:31], v[66:67] op_sel:[0,1]
	v_lshlrev_b32_e32 v36, 16, v162
	v_and_b32_e32 v37, 0xffff0000, v162
	v_lshlrev_b32_e32 v38, 16, v163
	v_and_b32_e32 v39, 0xffff0000, v163
	v_pk_mul_f32 v[38:39], v[160:161], v[38:39] op_sel_hi:[0,1]
	v_pk_mul_f32 v[36:37], v[160:161], v[36:37] op_sel_hi:[0,1]
	v_pk_mul_f32 v[30:31], v[126:127], v[30:31]
	v_pk_mul_f32 v[28:29], v[124:125], v[28:29]
	v_pk_fma_f32 v[30:31], v[38:39], v[212:213], v[30:31]
	v_pk_fma_f32 v[28:29], v[36:37], v[206:207], v[28:29]
	v_cndmask_b32_e32 v31, v31, v141, vcc
	v_cndmask_b32_e32 v30, v30, v141, vcc
	v_cndmask_b32_e32 v29, v29, v141, vcc
	v_cndmask_b32_e32 v28, v28, v141, vcc
	global_store_dwordx4 v[48:49], v[28:31], off offset:576 sc1
	ds_read2_b64 v[28:31], v161 offset0:160 offset1:176
	v_add_u32_e32 v36, 0xa0, v226
	v_ashrrev_i32_e32 v37, 31, v36
	v_lshlrev_b32_e32 v38, 16, v158
	v_and_b32_e32 v39, 0xffff0000, v158
	v_lshlrev_b32_e32 v40, 16, v159
	v_and_b32_e32 v41, 0xffff0000, v159
	s_waitcnt lgkmcnt(0)
	v_pk_mul_f32 v[32:33], v[32:33], v[28:29] op_sel:[0,1]
	v_pk_mul_f32 v[34:35], v[34:35], v[28:29] op_sel:[0,1]
	v_pk_mul_f32 v[40:41], v[150:151], v[40:41] op_sel_hi:[0,1]
	v_pk_mul_f32 v[38:39], v[150:151], v[38:39] op_sel_hi:[0,1]
	v_pk_mul_f32 v[34:35], v[138:139], v[34:35]
	v_pk_mul_f32 v[32:33], v[136:137], v[32:33]
	v_lshlrev_b64 v[36:37], 12, v[36:37]
	v_pk_fma_f32 v[32:33], v[38:39], v[190:191], v[32:33]
	v_pk_fma_f32 v[34:35], v[40:41], v[192:193], v[34:35]
	v_lshl_add_u64 v[36:37], s[64:65], 0, v[36:37]
	v_cndmask_b32_e32 v35, v35, v141, vcc
	v_cndmask_b32_e32 v34, v34, v141, vcc
	v_cndmask_b32_e32 v33, v33, v141, vcc
	v_cndmask_b32_e32 v32, v32, v141, vcc
	v_lshl_add_u64 v[36:37], v[36:37], 0, v[172:173]
	global_store_dwordx4 v[36:37], v[32:35], off sc1
	v_pk_mul_f32 v[24:25], v[24:25], v[28:29] op_sel:[0,1]
	v_pk_mul_f32 v[26:27], v[26:27], v[28:29] op_sel:[0,1]
	v_lshlrev_b32_e32 v32, 16, v156
	v_and_b32_e32 v33, 0xffff0000, v156
	v_lshlrev_b32_e32 v34, 16, v157
	v_and_b32_e32 v35, 0xffff0000, v157
	v_pk_mul_f32 v[34:35], v[150:151], v[34:35] op_sel_hi:[0,1]
	v_pk_mul_f32 v[32:33], v[150:151], v[32:33] op_sel_hi:[0,1]
	v_pk_mul_f32 v[26:27], v[134:135], v[26:27]
	v_pk_mul_f32 v[24:25], v[132:133], v[24:25]
	v_pk_fma_f32 v[26:27], v[34:35], v[196:197], v[26:27]
	v_pk_fma_f32 v[24:25], v[32:33], v[188:189], v[24:25]
	v_cndmask_b32_e32 v27, v27, v141, vcc
	v_cndmask_b32_e32 v26, v26, v141, vcc
	v_cndmask_b32_e32 v25, v25, v141, vcc
	v_cndmask_b32_e32 v24, v24, v141, vcc
	global_store_dwordx4 v[36:37], v[24:27], off offset:64 sc1
	v_pk_mul_f32 v[20:21], v[20:21], v[28:29] op_sel:[0,1]
	v_pk_mul_f32 v[22:23], v[22:23], v[28:29] op_sel:[0,1]
	v_lshlrev_b32_e32 v24, 16, v154
	v_and_b32_e32 v25, 0xffff0000, v154
	v_lshlrev_b32_e32 v26, 16, v155
	v_and_b32_e32 v27, 0xffff0000, v155
	v_pk_mul_f32 v[26:27], v[150:151], v[26:27] op_sel_hi:[0,1]
	v_pk_mul_f32 v[24:25], v[150:151], v[24:25] op_sel_hi:[0,1]
	v_pk_mul_f32 v[22:23], v[130:131], v[22:23]
	v_pk_mul_f32 v[20:21], v[128:129], v[20:21]
	v_pk_fma_f32 v[22:23], v[26:27], v[204:205], v[22:23]
	v_pk_fma_f32 v[20:21], v[24:25], v[198:199], v[20:21]
	v_cndmask_b32_e32 v23, v23, v141, vcc
	v_cndmask_b32_e32 v22, v22, v141, vcc
	v_cndmask_b32_e32 v21, v21, v141, vcc
	v_cndmask_b32_e32 v20, v20, v141, vcc
	global_store_dwordx4 v[36:37], v[20:23], off offset:512 sc1
	v_pk_mul_f32 v[12:13], v[12:13], v[28:29] op_sel:[0,1]
	v_pk_mul_f32 v[14:15], v[14:15], v[28:29] op_sel:[0,1]
	v_lshlrev_b32_e32 v20, 16, v152
	v_and_b32_e32 v21, 0xffff0000, v152
	v_lshlrev_b32_e32 v22, 16, v153
	v_and_b32_e32 v23, 0xffff0000, v153
	v_pk_mul_f32 v[22:23], v[150:151], v[22:23] op_sel_hi:[0,1]
	v_pk_mul_f32 v[20:21], v[150:151], v[20:21] op_sel_hi:[0,1]
	v_pk_mul_f32 v[14:15], v[126:127], v[14:15]
	v_pk_mul_f32 v[12:13], v[124:125], v[12:13]
	v_pk_fma_f32 v[14:15], v[22:23], v[212:213], v[14:15]
	v_pk_fma_f32 v[12:13], v[20:21], v[206:207], v[12:13]
	v_cndmask_b32_e32 v15, v15, v141, vcc
	v_cndmask_b32_e32 v14, v14, v141, vcc
	v_cndmask_b32_e32 v13, v13, v141, vcc
	v_cndmask_b32_e32 v12, v12, v141, vcc
	global_store_dwordx4 v[36:37], v[12:15], off offset:576 sc1
	v_add_u32_e32 v20, 0xb0, v226
	v_pk_mul_f32 v[16:17], v[16:17], v[30:31] op_sel:[0,1]
	v_lshlrev_b32_e32 v12, 16, v148
	v_and_b32_e32 v13, 0xffff0000, v148
	v_ashrrev_i32_e32 v21, 31, v20
	v_lshlrev_b32_e32 v14, 16, v149
	v_and_b32_e32 v15, 0xffff0000, v149
	v_pk_mul_f32 v[12:13], v[140:141], v[12:13] op_sel_hi:[0,1]
	v_pk_mul_f32 v[18:19], v[18:19], v[30:31] op_sel:[0,1]
	v_pk_mul_f32 v[16:17], v[136:137], v[16:17]
	v_pk_mul_f32 v[14:15], v[140:141], v[14:15] op_sel_hi:[0,1]
	v_pk_mul_f32 v[18:19], v[138:139], v[18:19]
	v_pk_fma_f32 v[12:13], v[12:13], v[190:191], v[16:17]
	v_lshlrev_b64 v[16:17], 12, v[20:21]
	v_pk_fma_f32 v[14:15], v[14:15], v[192:193], v[18:19]
	v_lshl_add_u64 v[16:17], s[64:65], 0, v[16:17]
	v_cndmask_b32_e32 v15, v15, v141, vcc
	v_cndmask_b32_e32 v14, v14, v141, vcc
	v_cndmask_b32_e32 v13, v13, v141, vcc
	v_cndmask_b32_e32 v12, v12, v141, vcc
	v_lshl_add_u64 v[16:17], v[16:17], 0, v[172:173]
	global_store_dwordx4 v[16:17], v[12:15], off sc1
	v_pk_mul_f32 v[8:9], v[8:9], v[30:31] op_sel:[0,1]
	v_pk_mul_f32 v[10:11], v[10:11], v[30:31] op_sel:[0,1]
	v_lshlrev_b32_e32 v12, 16, v146
	v_and_b32_e32 v13, 0xffff0000, v146
	v_lshlrev_b32_e32 v14, 16, v147
	v_and_b32_e32 v15, 0xffff0000, v147
	v_pk_mul_f32 v[14:15], v[140:141], v[14:15] op_sel_hi:[0,1]
	v_pk_mul_f32 v[12:13], v[140:141], v[12:13] op_sel_hi:[0,1]
	v_pk_mul_f32 v[10:11], v[134:135], v[10:11]
	v_pk_mul_f32 v[8:9], v[132:133], v[8:9]
	v_pk_fma_f32 v[10:11], v[14:15], v[196:197], v[10:11]
	v_pk_fma_f32 v[8:9], v[12:13], v[188:189], v[8:9]
	v_cndmask_b32_e32 v11, v11, v141, vcc
	v_cndmask_b32_e32 v10, v10, v141, vcc
	v_cndmask_b32_e32 v9, v9, v141, vcc
	v_cndmask_b32_e32 v8, v8, v141, vcc
	global_store_dwordx4 v[16:17], v[8:11], off offset:64 sc1
	v_pk_mul_f32 v[4:5], v[4:5], v[30:31] op_sel:[0,1]
	v_pk_mul_f32 v[6:7], v[6:7], v[30:31] op_sel:[0,1]
	v_lshlrev_b32_e32 v8, 16, v144
	v_and_b32_e32 v9, 0xffff0000, v144
	v_lshlrev_b32_e32 v10, 16, v145
	v_and_b32_e32 v11, 0xffff0000, v145
	v_pk_mul_f32 v[10:11], v[140:141], v[10:11] op_sel_hi:[0,1]
	v_pk_mul_f32 v[8:9], v[140:141], v[8:9] op_sel_hi:[0,1]
	v_pk_mul_f32 v[6:7], v[130:131], v[6:7]
	v_pk_mul_f32 v[4:5], v[128:129], v[4:5]
	v_pk_fma_f32 v[6:7], v[10:11], v[204:205], v[6:7]
	v_pk_fma_f32 v[4:5], v[8:9], v[198:199], v[4:5]
	v_cndmask_b32_e32 v7, v7, v141, vcc
	v_cndmask_b32_e32 v6, v6, v141, vcc
	v_cndmask_b32_e32 v5, v5, v141, vcc
	v_cndmask_b32_e32 v4, v4, v141, vcc
	global_store_dwordx4 v[16:17], v[4:7], off offset:512 sc1
	v_pk_mul_f32 v[0:1], v[0:1], v[30:31] op_sel:[0,1]
	v_pk_mul_f32 v[2:3], v[2:3], v[30:31] op_sel:[0,1]
	v_lshlrev_b32_e32 v4, 16, v142
	v_and_b32_e32 v5, 0xffff0000, v142
	v_lshlrev_b32_e32 v6, 16, v143
	v_and_b32_e32 v7, 0xffff0000, v143
	v_pk_mul_f32 v[6:7], v[140:141], v[6:7] op_sel_hi:[0,1]
	v_pk_mul_f32 v[4:5], v[140:141], v[4:5] op_sel_hi:[0,1]
	v_pk_mul_f32 v[2:3], v[126:127], v[2:3]
	v_pk_mul_f32 v[0:1], v[124:125], v[0:1]
	v_pk_fma_f32 v[2:3], v[6:7], v[212:213], v[2:3]
	v_pk_fma_f32 v[0:1], v[4:5], v[206:207], v[0:1]
	v_cndmask_b32_e32 v3, v3, v141, vcc
	v_cndmask_b32_e32 v2, v2, v141, vcc
	v_cndmask_b32_e32 v1, v1, v141, vcc
	v_cndmask_b32_e32 v0, v0, v141, vcc
	global_store_dwordx4 v[16:17], v[0:3], off offset:576 sc1
